# workgroups without a late tile go straight to attention+decode; late workgroups take conversions and SSD-state queues; P4 fac prefix via one load + DPP scan
# speedup vs baseline: 1.0656x; 1.0368x over previous
; #define LAS __attribute__((address_space(3)))
; __global__ void __launch_bounds__(512, 2) hymba_fwd(Params p) {
;     ...
;         {
;             const int nfull = (MROWS / 256) * (NPAD / 256) + (MMEM / 256) * (1024 / 256) - ((MROWS / 256) * (NPAD / 256) + (MMEM / 256) * (1024 / 256)) / G * G;
;             const int first_idle = (nfull == 0) ? 0 : nfull, nidle = G - first_idle;
;             if (bx >= first_idle) {
;                 const int lane = tid & 63, wave = __builtin_amdgcn_readfirstlane(tid >> 6);
;                 tr_pipeline(p, (LAS float*)(lds + wave * 16896), lane, (bx - first_idle) * 8 + wave, nidle * 8, NITEMS_P0, NITEMS_ALL);
;                 cache_mem_convert(p, (bx - first_idle) * 512 + tid, nidle * 512);
;             }
.LBB0_458:
	s_cmp_eq_u32 s98, 0
	s_cbranch_scc1 .LBB0_576
	v_readlane_b32 s0, v254, 2
	s_abs_i32 s0, s0
	s_sub_i32 s1, 0, s0
	s_waitcnt vmcnt(0)
	v_cvt_f32_u32_e32 v2, s0
	v_rcp_iflag_f32_e32 v2, v2
	s_nop 0
	v_mul_f32_e32 v2, 0x4f7ffffe, v2
	v_cvt_u32_f32_e32 v2, v2
	s_nop 0
	v_readfirstlane_b32 s2, v2
	s_mul_i32 s1, s1, s2
	s_mul_hi_u32 s1, s2, s1
	s_add_i32 s2, s2, s1
	s_mul_hi_u32 s1, s2, 0x38b
	s_mul_i32 s1, s1, s0
	s_sub_i32 s1, 0x38b, s1
	s_sub_i32 s2, s1, s0
	s_cmp_ge_u32 s1, s0
	s_cselect_b32 s1, s2, s1
	s_sub_i32 s2, s1, s0
	s_cmp_ge_u32 s1, s0
	s_cselect_b32 s2, s2, s1
	s_mov_b32 s2, 0
	s_cmpk_gt_i32 s95, 0x93
	s_cbranch_scc1 .LBB0_576
	s_cmp_lt_i32 s95, s2
	s_cbranch_scc1 .LBB0_576
	v_readfirstlane_b32 s0, v0
	s_sub_i32 s20, s95, s2
	s_lshr_b32 s4, s0, 6
	s_lshl_b32 s0, s20, 3
	v_and_b32_e32 v4, 63, v0
	s_add_i32 s3, s4, s0
	s_cmpk_lt_u32 s3, 0x400
	v_lshrrev_b32_e32 v2, 5, v4
	v_lshrrev_b32_e32 v3, 1, v0
	s_cbranch_scc1 .LBB0_461
	v_and_b32_e32 v140, 0x7c, v166
	v_lshrrev_b32_e32 v141, 5, v4
	v_and_b32_e32 v134, 24, v3
	v_mov_b32_e32 v135, 0
	s_mov_b64 s[0:1], 0
	v_mov_b64_e32 v[136:137], 0
	s_andn2_b64 vcc, exec, s[0:1]
	v_mov_b64_e32 v[4:5], 0
	s_cbranch_vccnz .LBB0_463
	s_branch .LBB0_462

; #define LAS __attribute__((address_space(3)))
; __device__ __forceinline__ void tr_pipeline(const Params& p, LAS float* scr, int lane, int gw, int NGW, int first, int end) {
;     f32x4 va[16], vb[16];
;     int it = first + gw;
;     TrItem ta{}, tb{};
;     if (it < end) { ta = tr_item(p, it, lane); tr_load(ta, tr_nsrc(it), va); }
; __global__ void __launch_bounds__(512, 2) hymba_fwd(Params p) {
;     ...
;             if (bx >= first_idle) {
;                 const int lane = tid & 63, wave = __builtin_amdgcn_readfirstlane(tid >> 6);
;                 tr_pipeline(p, (LAS float*)(lds + wave * 16896), lane, (bx - first_idle) * 8 + wave, nidle * 8, NITEMS_P0, NITEMS_ALL);
;                 cache_mem_convert(p, (bx - first_idle) * 512 + tid, nidle * 512);
.LBB0_463:
	v_readlane_b32 s0, v254, 2
	s_mulk_i32 s4, 0x4200
	s_sub_i32 s21, s0, s2
	s_movk_i32 s21, 0x94
	s_add_i32 s0, s4, 0
	v_lshl_add_u32 v2, v140, 2, s0
	v_mul_i32_i24_e32 v3, 0x210, v141
	v_mul_u32_u24_e32 v50, 0x210, v134
	v_lshlrev_b32_e32 v51, 2, v1
	s_mov_b32 s1, 0
	s_lshl_b32 s22, s21, 3
	s_add_i32 s23, s3, 0xf80
	v_add3_u32 v142, s0, v50, v51
	s_movk_i32 s24, 0x15ff
	s_movk_i32 s26, 0x1a08
	s_movk_i32 s27, 0x800
	s_mov_b32 s28, 0x10000
	s_mov_b32 s29, 0x20000
	s_mov_b32 s30, 0x30000
	s_mov_b32 s31, 0x40000
	s_mov_b32 s33, 0x50000
	s_mov_b32 s34, 0x60000
	v_add_u32_e32 v143, v2, v3
	v_mov_b32_e32 v2, 0
	s_branch .LBB0_467

; #define LAS __attribute__((address_space(3)))
; #define PSTAMP(i) do { if (PROBE_SEG >= 20 && blockIdx.x == PROBE_BLK && threadIdx.x == 0) ((volatile LAS unsigned long long*)(ctlw + 32))[8 + (i)] = __builtin_amdgcn_s_memrealtime(); } while (0)
; #define QUEUE_LOOP(qi, total, ...) for (;;) { __syncthreads(); if (threadIdx.x == 0) ctlw[16] = __hip_atomic_fetch_add(qbase + 64 * (qi), 1u, __ATOMIC_RELAXED, __HIP_MEMORY_SCOPE_AGENT); \
;         __syncthreads(); const int u = (int)ctlw[16]; if (u >= (total)) break; __VA_ARGS__ }
; template <int MASK> __device__ __forceinline__ void phase3(const Params& p, LAS unsigned char* lds, volatile LAS unsigned* ctlw, int qset) {
;     unsigned* qbase = (unsigned*)(p.ws + WS_CTL) + CW_QUEUE + 1024 * qset;
;     const bf16_t* PROJ = (const bf16_t*)(p.ws + WS_PROJ);
;     bf16_t* MIX = (bf16_t*)(p.ws + WS_MIX);
;     PSTAMP(4);
;     QUEUE_LOOP(0, U_SSDP, { ssd_state_unit<false>(p.ws, p.in[I_ALOG], p.in[I_SCONV], p.in[I_CONVW], p.in[I_CONVB], lds, u >> 5, (u >> 1) & 15, u & 1); })
;     QUEUE_LOOP(4, U_SSDSS, { ssd_state_unit<true>(p.ws, p.in[I_ALOG], p.in[I_SCONV], p.in[I_CONVW], p.in[I_CONVB], lds, u >> 1, 0, u & 1);
;         for (int hh = 0; hh < 4; ++hh)
;             ssd_out_unit<true>(p.ws, p.out, p.in[I_ALOG], p.in[I_DSKIP], p.in[I_SSDNW], p.in[I_SSM], p.in[I_SCONV], p.in[I_CONVW], p.in[I_CONVB], lds, u >> 1, 0, (u & 1) * 4 + hh); })
;     PSTAMP(5);
;     const unsigned gb0 = __builtin_amdgcn_readfirstlane(ctlw[20]);
.Lp3_enter:
	s_cmp_gt_i32 s6, 3
	s_cselect_b64 s[0:1], -1, 0
	s_cmp_lt_i32 s7, 4
	s_cselect_b64 s[2:3], -1, 0
	s_or_b64 s[0:1], s[0:1], s[2:3]
	s_and_b64 vcc, exec, s[0:1]
	v_mbcnt_lo_u32_b32 v190, -1, 0
	s_cbranch_vccnz .LBB0_1051
	s_add_u32 s48, s90, 0x5a00000
	s_addc_u32 s49, s91, 0
	s_add_u32 s12, s90, 0xd200000
	s_addc_u32 s13, s91, 0
	s_add_u32 s70, s90, 0x16200000
	s_addc_u32 s71, s91, 0
	s_add_u32 s14, s90, 0x13c00000
	s_addc_u32 s15, s91, 0
	s_add_u32 s72, s90, 0x14e00000
	s_addc_u32 s73, s91, 0
	s_add_i32 s24, 0, 0x27e40
	v_mbcnt_hi_u32_b32 v191, -1, v190
	s_waitcnt vmcnt(0)
	v_bfrev_b32_e32 v2, 0.5
	s_mov_b32 s5, 0
	v_cmp_eq_u32_e64 s[0:1], 0, v0
	v_mov_b32_e32 v155, 0
	s_movk_i32 s33, 0x3600
	s_movk_i32 s74, 0x2000
	s_mov_b64 s[6:7], 0x2400
	s_movk_i32 s75, 0x80
	s_mov_b64 s[8:9], 0x1800
	s_movk_i32 s76, 0x1000
	s_mov_b64 s[10:11], 0x2800
	s_mov_b64 s[16:17], 0x3800
	s_movk_i32 s77, 0x3000
	s_movk_i32 s78, 0x110
	s_mov_b64 s[18:19], 0x1c00
	s_mov_b64 s[20:21], 0x2c00
	s_mov_b64 s[22:23], 0x3c00
	s_mov_b64 s[26:27], 0x1000
	s_mov_b64 s[28:29], 0x2000
	s_mov_b64 s[30:31], 0x3000
	v_mov_b32_e32 v178, s24
	v_and_b32_e32 v192, 64, v191
	v_add_u32_e32 v1, -1, v191
	v_add_u32_e32 v180, -2, v191
	v_add_u32_e32 v181, -4, v191
	v_add_u32_e32 v182, -8, v191
	v_add_u32_e32 v183, -16, v191
	v_subrev_u32_e32 v184, 32, v191
	v_lshl_or_b32 v179, v191, 2, v2
	v_mov_b32_e32 v185, 0x8800
	v_mov_b32_e32 v186, 0x9900
	v_mov_b32_e32 v187, 0xaa00
	v_mov_b32_e32 v188, 0xbb00
	v_mov_b32_e32 v189, 0xcc00
	v_mov_b32_e32 v193, 0xdd00
	v_mov_b32_e32 v194, 0xee00
	v_mov_b32_e32 v195, 0xff00
	v_readlane_b32 s4, v254, 9
	s_cmpk_gt_i32 s4, 0x93
	s_cbranch_scc1 .LBB0_835
	s_branch .LBB0_630

; #define QUEUE_LOOP(qi, total, ...) for (;;) { __syncthreads(); if (threadIdx.x == 0) ctlw[16] = __hip_atomic_fetch_add(qbase + 64 * (qi), 1u, __ATOMIC_RELAXED, __HIP_MEMORY_SCOPE_AGENT); \
;         __syncthreads(); const int u = (int)ctlw[16]; if (u >= (total)) break; __VA_ARGS__ }
; template <bool SAMPLE> ...
;     ...
;     __syncthreads();
;     if (wid == 0) {
;         float d0 = (lane < NTOK) ? DTS[(size_t)(rowbase + lane) * 8 + h] : 0.f, d1 = (lane + 64 < NTOK) ? DTS[(size_t)(rowbase + lane + 64) * 8 + h] : 0.f;
;         float c0 = d0 * a_h, c1 = d1 * a_h;
;         scan128(c0, c1, lane);
;         csf[lane] = c0; csf[lane + 64] = c1; dtf[lane] = d0; dtf[lane + 64] = d1;
;     } else if (wid == 1 && !SAMPLE) {
;         if (lane < 16) { float sacc = 0.f; for (int q = lane + 1; q < c; ++q) sacc += SUMDT[(bs * 8 + h) * 16 + q]; facf[lane] = __expf(sacc); }
;     }
; __device__ __forceinline__ void phase4(const Params& p, LAS unsigned char* lds, volatile LAS unsigned* ctlw, int vcu, int G, int qset) {
;     ...
;     QUEUE_LOOP(5, NBATCH * 16 * 8, { const int v = NBATCH * 16 * 8 - 1 - u;
;         ssd_out_unit<false>(p.ws, p.out, p.in[I_ALOG], p.in[I_DSKIP], p.in[I_SSDNW], p.in[I_SSM], p.in[I_SCONV], p.in[I_CONVW], p.in[I_CONVB], lds, (v >> 3) & 3, v >> 5, v & 7); })
.LBB0_1081:
	s_or_b64 exec, exec, s[2:3]
	s_waitcnt lgkmcnt(0)
	s_barrier
	ds_read_b32 v2, v1
	s_mov_b64 s[2:3], -1
	s_waitcnt lgkmcnt(0)
	v_cmp_lt_i32_e32 vcc, s30, v2
	v_readfirstlane_b32 s73, v2
	s_cbranch_vccnz .LBB0_1076
	s_sub_i32 s74, 0x1ff, s73
	s_and_b32 s70, s74, 7
	s_lshl_b32 s20, s70, 2
	v_mov_b32_e32 v88, v0
	v_mov_b32_e32 v2, s20
	global_load_dword v4, v2, s[56:57]
	global_load_dword v53, v2, s[58:59]
	v_readfirstlane_b32 s21, v88
	s_lshr_b32 s72, s74, 5
	s_ashr_i32 s4, s21, 6
	v_and_b32_e32 v86, 63, v88
	s_and_b32 s71, s74, 31
	s_cmp_gt_u32 s21, 63
	v_cmp_gt_u32_e32 vcc, 16, v86
	s_barrier
	s_cbranch_scc0 .LBB0_1090
	s_cmp_eq_u32 s4, 1
	s_cselect_b64 s[2:3], -1, 0
	s_and_b64 s[22:23], s[2:3], vcc
	s_and_saveexec_b64 s[2:3], s[22:23]
	s_cbranch_execz .LBB0_1089
	v_add_u32_e32 v5, 1, v86
	v_cmp_gt_u32_e32 vcc, s72, v5
	s_lshl_b32 s21, s71, 4
	v_add_lshl_u32 v50, s21, v86, 2
	v_mov_b32_e32 v6, 0
	s_and_saveexec_b64 s[22:23], vcc
	s_cbranch_execz .Lfac_noload
	global_load_dword v6, v50, s[16:17]
.Lfac_noload:
	s_or_b64 exec, exec, s[22:23]
	s_waitcnt vmcnt(0)
	s_nop 1
	v_add_f32_dpp v6, v6, v6 row_shl:1 row_mask:0xf bank_mask:0xf bound_ctrl:1
	s_nop 1
	v_add_f32_dpp v6, v6, v6 row_shl:2 row_mask:0xf bank_mask:0xf bound_ctrl:1
	s_nop 1
	v_add_f32_dpp v6, v6, v6 row_shl:4 row_mask:0xf bank_mask:0xf bound_ctrl:1
	s_nop 1
	v_add_f32_dpp v6, v6, v6 row_shl:8 row_mask:0xf bank_mask:0xf bound_ctrl:1
	v_mul_f32_e32 v2, 0x3fb8aa3b, v6
